# weight bf16-copy conversion re-scheduled: FFN1-up tail keeps W_down1+W_in, scan phase (blocks without long chain) converts W_out+W_gu2, FFN2-up idle half-round converts W_down2
# speedup vs baseline: 1.0434x; 1.0024x over previous
.LBB0_136:
	s_ashr_i32 s4, s31, 1
	s_cmp_lt_i32 s30, s4
	s_cbranch_scc1 .LBB0_182
	s_sub_i32 s5, s30, s4
	s_waitcnt vmcnt(0)
	v_ashrrev_i32_e32 v0, 6, v146
	v_lshl_add_u32 v1, s5, 3, v0
	s_movk_i32 s5, 0xa00
	v_cmp_gt_i32_e32 vcc, s5, v1
	s_and_saveexec_b64 s[12:13], vcc
	s_cbranch_execz .LBB0_181
	v_and_b32_e32 v2, 7, v146
	v_mov_b32_e32 v35, 0
	v_lshlrev_b32_e32 v34, 4, v2
	v_lshlrev_b32_e32 v32, 2, v2
	v_lshlrev_b32_e32 v36, 3, v2
	v_mul_u32_u24_e32 v6, 0x420, v2
	v_lshl_add_u64 v[2:3], v[144:145], 0, v[34:35]
	s_mov_b64 s[6:7], 0x1580000
	v_lshl_add_u64 v[38:39], v[2:3], 0, s[6:7]
	s_load_dwordx2 s[6:7], s[0:1], 0x70
	s_load_dwordx4 s[8:11], s[0:1], 0x30
	s_sub_i32 s5, s31, s4
	s_lshl_b32 s33, s5, 3
	s_movk_i32 s5, 0x2100
	v_add_u32_e32 v33, 0xb00, v1
	v_mul_lo_u32 v1, v0, s5
	v_add_u32_e32 v1, 0, v1
	v_bfe_u32 v37, v146, 3, 3
	s_mov_b64 s[14:15], 0x1080000
	s_waitcnt lgkmcnt(0)
	s_cmp_lg_u64 s[8:9], 0
	v_add_u32_e32 v4, v1, v34
	v_mul_u32_u24_e32 v5, 0x84, v37
	v_lshl_add_u64 v[40:41], v[2:3], 0, s[14:15]
	s_cselect_b64 s[14:15], -1, 0
	v_lshl_add_u32 v0, s30, 3, v0
	s_lshl_b32 s4, s4, 3
	v_lshlrev_b32_e32 v7, 2, v37
	v_subrev_u32_e32 v0, s4, v0
	v_add_u32_e32 v57, v4, v5
	s_movk_i32 s34, 0xb00
	v_or_b32_e32 v52, 8, v37
	v_or_b32_e32 v53, 16, v37
	v_or_b32_e32 v54, 24, v37
	v_add3_u32 v55, v1, v6, v7
	v_lshl_add_u64 v[42:43], s[6:7], 0, v[34:35]
	v_lshl_add_u64 v[44:45], s[10:11], 0, v[34:35]
	s_mov_b64 s[10:11], 0
	v_add_u32_e32 v56, 0xffffe900, v0
	s_movk_i32 s35, 0x2200
	s_movk_i32 s36, 0xaff
	s_movk_i32 s37, 0x107f
	s_movk_i32 s38, 0x14ff
	s_movk_i32 s39, 0x16ff
	v_add_u32_e32 v58, 0x420, v57
	v_add_u32_e32 v59, 0x428, v57
	v_add_u32_e32 v60, 0x840, v57
	v_add_u32_e32 v61, 0x848, v57
	v_add_u32_e32 v62, 0xc60, v57
	v_add_u32_e32 v63, 0xc68, v57
	v_add_u32_e32 v64, 0x1080, v57
	v_add_u32_e32 v65, 0x1088, v57
	v_add_u32_e32 v66, 0x14a0, v57
	v_add_u32_e32 v67, 0x14a8, v57
	v_add_u32_e32 v68, 0x18c0, v57
	s_mov_b32 s40, 0x38e38e39
	s_movk_i32 s41, 0x48
	s_movk_i32 s42, 0x2480
	s_mov_b32 s43, 0x2e8ba2e9
	s_movk_i32 s44, 0xb0
	s_movk_i32 s45, 0xff80
	s_movk_i32 s46, 0x2c00
	s_movk_i32 s47, 0x14ff
	v_add_u32_e32 v69, 0x18c8, v57
	v_add_u32_e32 v70, 0x1ce0, v57
	v_add_u32_e32 v71, 0x1ce8, v57
	v_mov_b32_e32 v72, 0x90
	v_mov_b32_e32 v73, 0x2280000
	v_mov_b32_e32 v74, 0xb00000
	v_mov_b32_e32 v75, 0x78
	v_mov_b32_e32 v76, 0x1780000
	s_branch .LBB0_141

.LBB0_646:
	s_or_b64 exec, exec, s[8:9]
	s_sub_i32 s4, s24, 0xc0
	s_max_i32 s4, s4, 0
	s_addk_i32 s4, 0x80
	s_cmp_lt_u32 s2, 0x80
	s_cbranch_scc1 .Lcv2_lo
	s_cmp_lt_u32 s2, 0xc0
	s_cbranch_scc1 .Lcv2_exit
	s_sub_i32 s5, s2, 64
	s_branch .Lcv2_go
.Lcv2_lo:
	s_mov_b32 s5, s2
.Lcv2_go:
	s_add_i32 s30, s5, s4
	s_lshl_b32 s31, s4, 1
	v_mov_b32_e32 v146, v240
	s_load_dwordx2 s[4:5], s[0:1], 0xa8
	s_waitcnt lgkmcnt(0)
	v_mov_b64_e32 v[144:145], s[4:5]
.Lcv2_136:
	s_ashr_i32 s4, s31, 1
	s_cmp_lt_i32 s30, s4
	s_cbranch_scc1 .Lcv2_exit
	s_sub_i32 s5, s30, s4
	s_waitcnt vmcnt(0)
	v_ashrrev_i32_e32 v0, 6, v146
	v_lshl_add_u32 v1, s5, 3, v0
	s_movk_i32 s5, 0xd00
	v_cmp_gt_i32_e32 vcc, s5, v1
	s_and_saveexec_b64 s[12:13], vcc
	s_cbranch_execz .Lcv2_181
	v_and_b32_e32 v2, 7, v146
	v_mov_b32_e32 v35, 0
	v_lshlrev_b32_e32 v34, 4, v2
	v_lshlrev_b32_e32 v32, 2, v2
	v_lshlrev_b32_e32 v36, 3, v2
	v_mul_u32_u24_e32 v6, 0x420, v2
	v_lshl_add_u64 v[2:3], v[144:145], 0, v[34:35]
	s_mov_b64 s[6:7], 0x1580000
	v_lshl_add_u64 v[38:39], v[2:3], 0, s[6:7]
	s_load_dwordx2 s[6:7], s[0:1], 0x70
	s_load_dwordx4 s[8:11], s[0:1], 0x30
	s_sub_i32 s5, s31, s4
	s_lshl_b32 s33, s5, 3
	s_movk_i32 s5, 0x2100
	v_add_u32_e32 v33, 0x1500, v1
	v_mul_lo_u32 v1, v0, s5
	v_add_u32_e32 v1, 0, v1
	v_bfe_u32 v37, v146, 3, 3
	s_mov_b64 s[14:15], 0x1080000
	s_waitcnt lgkmcnt(0)
	s_cmp_lg_u64 s[8:9], 0
	v_add_u32_e32 v4, v1, v34
	v_mul_u32_u24_e32 v5, 0x84, v37
	v_lshl_add_u64 v[40:41], v[2:3], 0, s[14:15]
	s_cselect_b64 s[14:15], -1, 0
	v_lshl_add_u32 v0, s30, 3, v0
	s_lshl_b32 s4, s4, 3
	v_lshlrev_b32_e32 v7, 2, v37
	v_subrev_u32_e32 v0, s4, v0
	v_add_u32_e32 v57, v4, v5
	s_movk_i32 s34, 0xb00
	v_or_b32_e32 v52, 8, v37
	v_or_b32_e32 v53, 16, v37
	v_or_b32_e32 v54, 24, v37
	v_add3_u32 v55, v1, v6, v7
	v_lshl_add_u64 v[42:43], s[6:7], 0, v[34:35]
	v_lshl_add_u64 v[44:45], s[10:11], 0, v[34:35]
	s_mov_b64 s[10:11], 0
	v_add_u32_e32 v56, 0xfffff300, v0
	s_movk_i32 s35, 0x2200
	s_movk_i32 s36, 0xaff
	s_movk_i32 s37, 0x107f
	s_movk_i32 s38, 0x14ff
	s_movk_i32 s39, 0x16ff
	v_add_u32_e32 v58, 0x420, v57
	v_add_u32_e32 v59, 0x428, v57
	v_add_u32_e32 v60, 0x840, v57
	v_add_u32_e32 v61, 0x848, v57
	v_add_u32_e32 v62, 0xc60, v57
	v_add_u32_e32 v63, 0xc68, v57
	v_add_u32_e32 v64, 0x1080, v57
	v_add_u32_e32 v65, 0x1088, v57
	v_add_u32_e32 v66, 0x14a0, v57
	v_add_u32_e32 v67, 0x14a8, v57
	v_add_u32_e32 v68, 0x18c0, v57
	s_mov_b32 s40, 0x38e38e39
	s_movk_i32 s41, 0x48
	s_movk_i32 s42, 0x2480
	s_mov_b32 s43, 0x2e8ba2e9
	s_movk_i32 s44, 0xb0
	s_movk_i32 s45, 0xff80
	s_movk_i32 s46, 0x2c00
	s_movk_i32 s47, 0x21ff
	v_add_u32_e32 v69, 0x18c8, v57
	v_add_u32_e32 v70, 0x1ce0, v57
	v_add_u32_e32 v71, 0x1ce8, v57
	v_mov_b32_e32 v72, 0x90
	v_mov_b32_e32 v73, 0x2280000
	v_mov_b32_e32 v74, 0xb00000
	v_mov_b32_e32 v75, 0x78
	v_mov_b32_e32 v76, 0x1780000
	s_branch .Lcv2_141

.Lcv2_169:
	s_andn2_saveexec_b64 s[6:7], s[16:17]
	s_cbranch_execz .Lcv2_140
	v_mul_hi_i32 v1, v0, s43
	v_lshrrev_b32_e32 v2, 31, v1
	v_ashrrev_i32_e32 v1, 5, v1
	v_add_u32_e32 v4, v1, v2
	v_mul_lo_u32 v1, v4, s44
	v_sub_u32_e32 v5, v0, v1
	v_bfe_u32 v0, v5, 2, 1
	v_add_u32_e32 v1, 3, v0
	v_or_b32_e32 v0, 16, v0
	v_cndmask_b32_e64 v0, v0, v1, s[4:5]
	v_lshlrev_b32_e32 v0, 3, v0
	global_load_dwordx2 v[0:1], v0, s[0:1]
	v_lshlrev_b32_e32 v77, 5, v5
	v_lshlrev_b32_e32 v46, 6, v4
	v_lshlrev_b32_e32 v4, 4, v5
	v_and_b32_e32 v5, 0x60, v77
	v_cndmask_b32_e64 v34, v75, 16, s[4:5]
	v_and_or_b32 v4, v4, s45, v5
	v_lshl_add_u64 v[2:3], s[0:1], 0, v[34:35]
	v_ashrrev_i32_e32 v5, 31, v4
	v_lshlrev_b32_e32 v34, 2, v32
	global_load_dwordx2 v[50:51], v[2:3], off
	v_or_b32_e32 v48, v46, v37
	v_or_b32_e32 v6, 8, v48
	v_or_b32_e32 v7, 16, v48
	v_or_b32_e32 v8, 24, v48
	v_or_b32_e32 v9, 32, v48
	v_or_b32_e32 v10, 40, v48
	v_or_b32_e32 v11, 48, v48
	v_or_b32_e32 v12, 56, v48
	s_waitcnt vmcnt(1)
	v_lshl_add_u64 v[0:1], v[4:5], 2, v[0:1]
	v_lshl_add_u64 v[0:1], v[0:1], 0, v[34:35]
	v_mad_i64_i32 v[78:79], s[16:17], v48, s46, v[0:1]
	v_mad_i64_i32 v[80:81], s[16:17], v6, s46, v[0:1]
	v_mad_i64_i32 v[82:83], s[16:17], v7, s46, v[0:1]
	v_mad_i64_i32 v[84:85], s[16:17], v8, s46, v[0:1]
	v_mad_i64_i32 v[86:87], s[16:17], v9, s46, v[0:1]
	v_mad_i64_i32 v[88:89], s[16:17], v10, s46, v[0:1]
	v_mad_i64_i32 v[90:91], s[16:17], v11, s46, v[0:1]
	v_mad_i64_i32 v[92:93], s[16:17], v12, s46, v[0:1]
	global_load_dwordx4 v[28:31], v[78:79], off nt
	global_load_dwordx4 v[24:27], v[80:81], off nt
	global_load_dwordx4 v[20:23], v[82:83], off nt
	global_load_dwordx4 v[16:19], v[84:85], off nt
	global_load_dwordx4 v[12:15], v[86:87], off nt
	global_load_dwordx4 v[8:11], v[88:89], off nt
	global_load_dwordx4 v[4:7], v[90:91], off nt
	global_load_dwordx4 v[0:3], v[92:93], off nt
	s_waitcnt vmcnt(8)
	v_cmp_ne_u64_e32 vcc, 0, v[50:51]
	s_and_saveexec_b64 s[16:17], vcc
	s_cbranch_execz .Lcv2_139
	v_ashrrev_i32_e32 v49, 31, v48
	v_lshl_add_u64 v[48:49], v[48:49], 2, v[50:51]
	global_load_dword v34, v[48:49], off
	global_load_dword v50, v[48:49], off offset:32
	global_load_dword v78, v[48:49], off offset:64
	global_load_dword v80, v[48:49], off offset:96
	global_load_dword v82, v[48:49], off offset:128
	global_load_dword v84, v[48:49], off offset:160
	global_load_dword v86, v[48:49], off offset:192
	global_load_dword v88, v[48:49], off offset:224
	s_waitcnt vmcnt(7)
	v_pk_mul_f32 v[30:31], v[30:31], v[34:35] op_sel_hi:[1,0]
	v_pk_mul_f32 v[28:29], v[28:29], v[34:35] op_sel_hi:[1,0]
	s_waitcnt vmcnt(6)
	v_pk_mul_f32 v[26:27], v[26:27], v[50:51] op_sel_hi:[1,0]
	v_pk_mul_f32 v[24:25], v[24:25], v[50:51] op_sel_hi:[1,0]
	s_waitcnt vmcnt(5)
	v_pk_mul_f32 v[22:23], v[22:23], v[78:79] op_sel_hi:[1,0]
	v_pk_mul_f32 v[20:21], v[20:21], v[78:79] op_sel_hi:[1,0]
	s_waitcnt vmcnt(4)
	v_pk_mul_f32 v[18:19], v[18:19], v[80:81] op_sel_hi:[1,0]
	v_pk_mul_f32 v[16:17], v[16:17], v[80:81] op_sel_hi:[1,0]
	s_waitcnt vmcnt(3)
	v_pk_mul_f32 v[14:15], v[14:15], v[82:83] op_sel_hi:[1,0]
	v_pk_mul_f32 v[12:13], v[12:13], v[82:83] op_sel_hi:[1,0]
	s_waitcnt vmcnt(2)
	v_pk_mul_f32 v[10:11], v[10:11], v[84:85] op_sel_hi:[1,0]
	v_pk_mul_f32 v[8:9], v[8:9], v[84:85] op_sel_hi:[1,0]
	s_waitcnt vmcnt(1)
	v_pk_mul_f32 v[6:7], v[6:7], v[86:87] op_sel_hi:[1,0]
	v_pk_mul_f32 v[4:5], v[4:5], v[86:87] op_sel_hi:[1,0]
	s_waitcnt vmcnt(0)
	v_pk_mul_f32 v[2:3], v[2:3], v[88:89] op_sel_hi:[1,0]
	v_pk_mul_f32 v[0:1], v[0:1], v[88:89] op_sel_hi:[1,0]
	s_branch .Lcv2_139
.Lcv2_180:
	s_or_b64 exec, exec, s[10:11]
	s_load_dwordx2 s[4:5], s[0:1], 0xa8
	s_waitcnt lgkmcnt(0)
	v_mov_b64_e32 v[144:145], s[4:5]

.Lcv2_exit:
	s_load_dwordx4 s[4:7], s[0:1], 0xa0
	s_waitcnt lgkmcnt(0)
	v_mov_b32_e32 v0, s6
	v_mov_b32_e32 v1, s7
	s_waitcnt vmcnt(0)
	s_nop 0
	v_readfirstlane_b32 s6, v0
	v_readfirstlane_b32 s7, v1
	s_barrier
	s_and_saveexec_b64 s[4:5], s[22:23]
	s_cbranch_execz .LBB0_698
	s_add_i32 s9, 0, 0x24800
	v_mov_b32_e32 v0, s9
	s_getreg_b32 s8, hwreg(HW_REG_XCC_ID, 0, 4)
	s_waitcnt vmcnt(0) expcnt(0) lgkmcnt(0)
	ds_read_b32 v2, v0
	s_add_i32 s9, 0, 0x24804
	v_mov_b32_e32 v0, s9
	ds_read_b32 v0, v0
	s_and_b32 s33, s8, 15
	s_waitcnt lgkmcnt(1)
	v_cmp_ne_u32_e32 vcc, 0, v2
	s_cbranch_vccnz .LBB0_662
	s_mul_i32 s8, s25, s3
	s_waitcnt lgkmcnt(0)
	v_mul_lo_u32 v0, s8, v242
	s_add_u32 s8, s6, 0x37a9200
	s_addc_u32 s9, s7, 0
	s_add_u32 s10, s6, 0x37a9400
	s_addc_u32 s11, s7, 0
	s_add_u32 s12, s6, 0x37a9500
	s_addc_u32 s13, s7, 0
	s_add_u32 s14, s6, 0x37a9600
	s_addc_u32 s15, s7, 0
	s_add_u32 s16, s6, 0x37a9700
	s_addc_u32 s17, s7, 0
	s_add_u32 s18, s6, 0x37a9800
	s_addc_u32 s19, s7, 0
	s_add_u32 s20, s6, 0x37a9900
	s_addc_u32 s21, s7, 0
	s_add_u32 s26, s6, 0x37a9a00
	s_addc_u32 s27, s7, 0
	s_add_u32 s28, s6, 0x37a9b00
	s_addc_u32 s29, s7, 0
	s_add_u32 s30, s6, 0x37a9c00
	s_addc_u32 s31, s7, 0
	s_add_u32 s34, s6, 0x37a9d00
	s_addc_u32 s35, s7, 0
	s_add_u32 s36, s6, 0x37a9e00
	s_addc_u32 s37, s7, 0
	s_add_u32 s38, s6, 0x37a9f00
	s_addc_u32 s39, s7, 0
	s_add_u32 s40, s6, 0x37aa000
	s_addc_u32 s41, s7, 0
	s_add_u32 s42, s6, 0x37aa100
	s_addc_u32 s43, s7, 0
	s_add_u32 s44, s6, 0x37aa200
	s_addc_u32 s45, s7, 0
	s_add_u32 s46, s6, 0x37aa300
	s_addc_u32 s47, s7, 0
	s_mov_b32 s54, 1
	v_mov_b32_e32 v17, 0
	s_branch .LBB0_650

.LBB0_898:
	s_waitcnt vmcnt(0) lgkmcnt(0)
	s_mov_b32 s30, s2
	s_mov_b32 s31, s24
	v_mov_b32_e32 v146, v240
	s_load_dwordx2 s[4:5], s[0:1], 0xa8
	s_waitcnt lgkmcnt(0)
	v_mov_b64_e32 v[144:145], s[4:5]
.Lcv1_136:
	s_ashr_i32 s4, s31, 1
	s_cmp_lt_i32 s30, s4
	s_cbranch_scc1 .Lcv1_exit
	s_sub_i32 s5, s30, s4
	s_waitcnt vmcnt(0)
	v_ashrrev_i32_e32 v0, 6, v146
	v_lshl_add_u32 v1, s5, 3, v0
	s_movk_i32 s5, 0x580
	v_cmp_gt_i32_e32 vcc, s5, v1
	s_and_saveexec_b64 s[12:13], vcc
	s_cbranch_execz .Lcv1_181
	v_and_b32_e32 v2, 7, v146
	v_mov_b32_e32 v35, 0
	v_lshlrev_b32_e32 v34, 4, v2
	v_lshlrev_b32_e32 v32, 2, v2
	v_lshlrev_b32_e32 v36, 3, v2
	v_mul_u32_u24_e32 v6, 0x420, v2
	v_lshl_add_u64 v[2:3], v[144:145], 0, v[34:35]
	s_mov_b64 s[6:7], 0x1580000
	v_lshl_add_u64 v[38:39], v[2:3], 0, s[6:7]
	s_load_dwordx2 s[6:7], s[0:1], 0x70
	s_load_dwordx4 s[8:11], s[0:1], 0x30
	s_sub_i32 s5, s31, s4
	s_lshl_b32 s33, s5, 3
	s_movk_i32 s5, 0x2100
	v_add_u32_e32 v33, 0x2200, v1
	v_mul_lo_u32 v1, v0, s5
	v_add_u32_e32 v1, 0, v1
	v_bfe_u32 v37, v146, 3, 3
	s_mov_b64 s[14:15], 0x1080000
	s_waitcnt lgkmcnt(0)
	s_cmp_lg_u64 s[8:9], 0
	v_add_u32_e32 v4, v1, v34
	v_mul_u32_u24_e32 v5, 0x84, v37
	v_lshl_add_u64 v[40:41], v[2:3], 0, s[14:15]
	s_cselect_b64 s[14:15], -1, 0
	v_lshl_add_u32 v0, s30, 3, v0
	s_lshl_b32 s4, s4, 3
	v_lshlrev_b32_e32 v7, 2, v37
	v_subrev_u32_e32 v0, s4, v0
	v_add_u32_e32 v57, v4, v5
	s_movk_i32 s34, 0xb00
	v_or_b32_e32 v52, 8, v37
	v_or_b32_e32 v53, 16, v37
	v_or_b32_e32 v54, 24, v37
	v_add3_u32 v55, v1, v6, v7
	v_lshl_add_u64 v[42:43], s[6:7], 0, v[34:35]
	v_lshl_add_u64 v[44:45], s[10:11], 0, v[34:35]
	s_mov_b64 s[10:11], 0
	v_add_u32_e32 v56, 0x0, v0
	s_movk_i32 s35, 0x2200
	s_movk_i32 s36, 0xaff
	s_movk_i32 s37, 0x107f
	s_movk_i32 s38, 0x14ff
	s_movk_i32 s39, 0x16ff
	v_add_u32_e32 v58, 0x420, v57
	v_add_u32_e32 v59, 0x428, v57
	v_add_u32_e32 v60, 0x840, v57
	v_add_u32_e32 v61, 0x848, v57
	v_add_u32_e32 v62, 0xc60, v57
	v_add_u32_e32 v63, 0xc68, v57
	v_add_u32_e32 v64, 0x1080, v57
	v_add_u32_e32 v65, 0x1088, v57
	v_add_u32_e32 v66, 0x14a0, v57
	v_add_u32_e32 v67, 0x14a8, v57
	v_add_u32_e32 v68, 0x18c0, v57
	s_mov_b32 s40, 0x38e38e39
	s_movk_i32 s41, 0x48
	s_movk_i32 s42, 0x2480
	s_mov_b32 s43, 0x2e8ba2e9
	s_movk_i32 s44, 0xb0
	s_movk_i32 s45, 0xff80
	s_movk_i32 s46, 0x2c00
	s_movk_i32 s47, 0x277f
	v_add_u32_e32 v69, 0x18c8, v57
	v_add_u32_e32 v70, 0x1ce0, v57
	v_add_u32_e32 v71, 0x1ce8, v57
	v_mov_b32_e32 v72, 0x90
	v_mov_b32_e32 v73, 0x2280000
	v_mov_b32_e32 v74, 0xb00000
	v_mov_b32_e32 v75, 0x78
	v_mov_b32_e32 v76, 0x1780000
	s_branch .Lcv1_141

.Lcv1_169:
	s_andn2_saveexec_b64 s[6:7], s[16:17]
	s_cbranch_execz .Lcv1_140
	v_mul_hi_i32 v1, v0, s43
	v_lshrrev_b32_e32 v2, 31, v1
	v_ashrrev_i32_e32 v1, 5, v1
	v_add_u32_e32 v4, v1, v2
	v_mul_lo_u32 v1, v4, s44
	v_sub_u32_e32 v5, v0, v1
	v_bfe_u32 v0, v5, 2, 1
	v_add_u32_e32 v1, 3, v0
	v_or_b32_e32 v0, 16, v0
	v_cndmask_b32_e64 v0, v0, v1, s[4:5]
	v_lshlrev_b32_e32 v0, 3, v0
	global_load_dwordx2 v[0:1], v0, s[0:1]
	v_lshlrev_b32_e32 v77, 5, v5
	v_lshlrev_b32_e32 v46, 6, v4
	v_lshlrev_b32_e32 v4, 4, v5
	v_and_b32_e32 v5, 0x60, v77
	v_cndmask_b32_e64 v34, v75, 16, s[4:5]
	v_and_or_b32 v4, v4, s45, v5
	v_lshl_add_u64 v[2:3], s[0:1], 0, v[34:35]
	v_ashrrev_i32_e32 v5, 31, v4
	v_lshlrev_b32_e32 v34, 2, v32
	global_load_dwordx2 v[50:51], v[2:3], off
	v_or_b32_e32 v48, v46, v37
	v_or_b32_e32 v6, 8, v48
	v_or_b32_e32 v7, 16, v48
	v_or_b32_e32 v8, 24, v48
	v_or_b32_e32 v9, 32, v48
	v_or_b32_e32 v10, 40, v48
	v_or_b32_e32 v11, 48, v48
	v_or_b32_e32 v12, 56, v48
	s_waitcnt vmcnt(1)
	v_lshl_add_u64 v[0:1], v[4:5], 2, v[0:1]
	v_lshl_add_u64 v[0:1], v[0:1], 0, v[34:35]
	v_mad_i64_i32 v[78:79], s[16:17], v48, s46, v[0:1]
	v_mad_i64_i32 v[80:81], s[16:17], v6, s46, v[0:1]
	v_mad_i64_i32 v[82:83], s[16:17], v7, s46, v[0:1]
	v_mad_i64_i32 v[84:85], s[16:17], v8, s46, v[0:1]
	v_mad_i64_i32 v[86:87], s[16:17], v9, s46, v[0:1]
	v_mad_i64_i32 v[88:89], s[16:17], v10, s46, v[0:1]
	v_mad_i64_i32 v[90:91], s[16:17], v11, s46, v[0:1]
	v_mad_i64_i32 v[92:93], s[16:17], v12, s46, v[0:1]
	global_load_dwordx4 v[28:31], v[78:79], off nt
	global_load_dwordx4 v[24:27], v[80:81], off nt
	global_load_dwordx4 v[20:23], v[82:83], off nt
	global_load_dwordx4 v[16:19], v[84:85], off nt
	global_load_dwordx4 v[12:15], v[86:87], off nt
	global_load_dwordx4 v[8:11], v[88:89], off nt
	global_load_dwordx4 v[4:7], v[90:91], off nt
	global_load_dwordx4 v[0:3], v[92:93], off nt
	s_waitcnt vmcnt(8)
	v_cmp_ne_u64_e32 vcc, 0, v[50:51]
	s_and_saveexec_b64 s[16:17], vcc
	s_cbranch_execz .Lcv1_139
	v_ashrrev_i32_e32 v49, 31, v48
	v_lshl_add_u64 v[48:49], v[48:49], 2, v[50:51]
	global_load_dword v34, v[48:49], off
	global_load_dword v50, v[48:49], off offset:32
	global_load_dword v78, v[48:49], off offset:64
	global_load_dword v80, v[48:49], off offset:96
	global_load_dword v82, v[48:49], off offset:128
	global_load_dword v84, v[48:49], off offset:160
	global_load_dword v86, v[48:49], off offset:192
	global_load_dword v88, v[48:49], off offset:224
	s_waitcnt vmcnt(7)
	v_pk_mul_f32 v[30:31], v[30:31], v[34:35] op_sel_hi:[1,0]
	v_pk_mul_f32 v[28:29], v[28:29], v[34:35] op_sel_hi:[1,0]
	s_waitcnt vmcnt(6)
	v_pk_mul_f32 v[26:27], v[26:27], v[50:51] op_sel_hi:[1,0]
	v_pk_mul_f32 v[24:25], v[24:25], v[50:51] op_sel_hi:[1,0]
	s_waitcnt vmcnt(5)
	v_pk_mul_f32 v[22:23], v[22:23], v[78:79] op_sel_hi:[1,0]
	v_pk_mul_f32 v[20:21], v[20:21], v[78:79] op_sel_hi:[1,0]
	s_waitcnt vmcnt(4)
	v_pk_mul_f32 v[18:19], v[18:19], v[80:81] op_sel_hi:[1,0]
	v_pk_mul_f32 v[16:17], v[16:17], v[80:81] op_sel_hi:[1,0]
	s_waitcnt vmcnt(3)
	v_pk_mul_f32 v[14:15], v[14:15], v[82:83] op_sel_hi:[1,0]
	v_pk_mul_f32 v[12:13], v[12:13], v[82:83] op_sel_hi:[1,0]
	s_waitcnt vmcnt(2)
	v_pk_mul_f32 v[10:11], v[10:11], v[84:85] op_sel_hi:[1,0]
	v_pk_mul_f32 v[8:9], v[8:9], v[84:85] op_sel_hi:[1,0]
	s_waitcnt vmcnt(1)
	v_pk_mul_f32 v[6:7], v[6:7], v[86:87] op_sel_hi:[1,0]
	v_pk_mul_f32 v[4:5], v[4:5], v[86:87] op_sel_hi:[1,0]
	s_waitcnt vmcnt(0)
	v_pk_mul_f32 v[2:3], v[2:3], v[88:89] op_sel_hi:[1,0]
	v_pk_mul_f32 v[0:1], v[0:1], v[88:89] op_sel_hi:[1,0]
	s_branch .Lcv1_139
.Lcv1_180:
	s_or_b64 exec, exec, s[10:11]
	s_load_dwordx2 s[4:5], s[0:1], 0xa8
	s_waitcnt lgkmcnt(0)
	v_mov_b64_e32 v[144:145], s[4:5]

.Lcv1_exit:
	s_load_dwordx2 s[26:27], s[0:1], 0xa8
	s_waitcnt vmcnt(0) lgkmcnt(0)
	v_mov_b32_e32 v0, s26
	v_mov_b32_e32 v1, s27
	s_waitcnt vmcnt(0)
	s_nop 0
	v_readfirstlane_b32 s6, v0
	v_readfirstlane_b32 s7, v1
	s_barrier
	s_and_saveexec_b64 s[4:5], s[22:23]
	s_cbranch_execz .LBB0_958
	s_add_i32 s9, 0, 0x24800
	v_mov_b32_e32 v0, s9
	s_getreg_b32 s8, hwreg(HW_REG_XCC_ID, 0, 4)
	s_waitcnt vmcnt(0) expcnt(0) lgkmcnt(0)
	ds_read_b32 v2, v0
	s_add_i32 s9, 0, 0x24804
	v_mov_b32_e32 v0, s9
	ds_read_b32 v0, v0
	s_and_b32 s33, s8, 15
	s_waitcnt lgkmcnt(1)
	v_cmp_ne_u32_e32 vcc, 0, v2
	s_cbranch_vccnz .LBB0_922
	s_add_u32 s8, s6, 0x37a9200
	s_addc_u32 s9, s7, 0
	s_add_u32 s10, s6, 0x37a9400
	s_addc_u32 s11, s7, 0
	s_add_u32 s12, s6, 0x37a9500
	s_addc_u32 s13, s7, 0
	s_add_u32 s14, s6, 0x37a9600
	s_addc_u32 s15, s7, 0
	s_add_u32 s16, s6, 0x37a9700
	s_addc_u32 s17, s7, 0
	s_add_u32 s18, s6, 0x37a9800
	s_addc_u32 s19, s7, 0
	s_add_u32 s20, s6, 0x37a9900
	s_addc_u32 s21, s7, 0
	s_add_u32 s22, s6, 0x37a9a00
	s_addc_u32 s23, s7, 0
	s_add_u32 s26, s6, 0x37a9b00
	s_addc_u32 s27, s7, 0
	s_add_u32 s28, s6, 0x37a9c00
	s_addc_u32 s29, s7, 0
	s_add_u32 s30, s6, 0x37a9d00
	s_addc_u32 s31, s7, 0
	s_add_u32 s34, s6, 0x37a9e00
	s_addc_u32 s35, s7, 0
	s_add_u32 s36, s6, 0x37a9f00
	s_addc_u32 s37, s7, 0
	s_add_u32 s38, s6, 0x37aa000
	s_addc_u32 s39, s7, 0
	s_add_u32 s40, s6, 0x37aa100
	s_addc_u32 s41, s7, 0
	s_add_u32 s42, s6, 0x37aa200
	s_addc_u32 s43, s7, 0
	s_mul_i32 s3, s25, s3
	s_add_u32 s44, s6, 0x37aa300
	s_waitcnt lgkmcnt(0)
	v_mul_lo_u32 v0, s3, v242
	s_addc_u32 s45, s7, 0
	s_mov_b32 s3, 1
	v_mov_b32_e32 v17, 0
	s_branch .LBB0_902
